# ffn gate/up GEMM: counted vmcnt(8) at the first K step of each tile so the previous tile epilogue stores drain under that step's MFMAs
# baseline (speedup 1.0000x reference)
; #define RAW_BARRIER() do { asm volatile("s_waitcnt lgkmcnt(0)" ::: "memory"); __builtin_amdgcn_s_barrier(); } while (0)
;   DI u16* kt() const { return (u16*)(ws + O_KT); }
; template <class DescFn, class EpiFn>
; DI void gemm_stream(unsigned char* smem, const int wv, const int start, const int stride, const int end, const int ldb, const int nk, DescFn&& desc, EpiFn&& mkepi) {
;     ...
;   int cur_i = start;
;   TileDesc cur = desc(cur_i);
;   DMA(cur, 0, 0);
; #pragma unroll 1
;   while (true) {
;     const int nxt_i = cur_i + stride;
;     const bool has_next = nxt_i < end;
;     TileDesc nxt = cur;
;     if (has_next) nxt = desc(nxt_i);
;     f32x16 acc[2][4];
; #pragma unroll
;     for (int a = 0; a < 2; ++a)
; #pragma unroll
;       for (int b = 0; b < 4; ++b) zero_acc(acc[a][b]);
;     bf16x8 Fw0, Fw1, Ft0, Ft1, Ft2, Ft3, Gw0, Gw1, Gt0, Gt1, Gt2, Gt3;
; #pragma unroll 1
;     for (int kt = 0; kt < nk; ++kt) {
;       const int buf = kt & 1;
;       asm volatile("s_waitcnt vmcnt(0)" ::: "memory");
;       RAW_BARRIER();
.LBB0_181:
	v_lshl_add_u64 v[0:1], s[6:7], 0, v[152:153]
	v_mov_b32_e32 v159, v165
	v_lshl_add_u64 v[2:3], s[8:9], 0, v[152:153]
	v_lshl_add_u64 v[162:163], v[0:1], 0, v[164:165]
	v_lshl_add_u64 v[0:1], v[0:1], 0, v[158:159]
	s_mov_b64 s[18:19], 0x4000
	s_mov_b64 s[24:25], 0xc000
	s_mov_b64 s[28:29], 0x14000
	s_mov_b64 s[34:35], 0x1c000
	v_lshl_add_u64 v[168:169], v[0:1], 0, s[18:19]
	v_lshl_add_u64 v[172:173], v[0:1], 0, s[24:25]
	v_lshl_add_u64 v[176:177], v[0:1], 0, s[28:29]
	v_lshl_add_u64 v[180:181], v[0:1], 0, s[34:35]
	v_lshl_add_u64 v[0:1], v[2:3], 0, v[158:159]
	s_mov_b64 s[22:23], 0x8000
	s_mov_b64 s[26:27], 0x10000
	s_mov_b64 s[30:31], 0x18000
	v_lshl_add_u64 v[182:183], v[2:3], 0, v[164:165]
	v_lshl_add_u64 v[184:185], v[0:1], 0, s[18:19]
	v_lshl_add_u64 v[188:189], v[0:1], 0, s[24:25]
	v_lshl_add_u64 v[192:193], v[0:1], 0, s[28:29]
	v_lshl_add_u64 v[196:197], v[0:1], 0, s[34:35]
	v_mov_b32_e32 v0, 0
	v_lshl_add_u64 v[170:171], v[162:163], 0, s[22:23]
	v_lshl_add_u64 v[174:175], v[162:163], 0, s[26:27]
	v_lshl_add_u64 v[178:179], v[162:163], 0, s[30:31]
	v_lshl_add_u64 v[186:187], v[182:183], 0, s[22:23]
	v_lshl_add_u64 v[190:191], v[182:183], 0, s[26:27]
	v_lshl_add_u64 v[194:195], v[182:183], 0, s[30:31]
	v_lshl_add_u64 v[198:199], s[12:13], 0, v[154:155]
	v_lshl_add_u64 v[200:201], s[12:13], 0, v[156:157]
	v_lshl_add_u64 v[202:203], s[10:11], 0, v[156:157]
	v_lshl_add_u64 v[204:205], s[10:11], 0, v[154:155]
	s_mov_b32 s18, 0
	s_mov_b64 s[10:11], 0
	v_mov_b32_e32 v1, v0
	v_mov_b32_e32 v2, v0
	v_mov_b32_e32 v3, v0
	v_mov_b32_e32 v4, v0
	v_mov_b32_e32 v5, v0
	v_mov_b32_e32 v6, v0
	v_mov_b32_e32 v7, v0
	v_mov_b32_e32 v8, v0
	v_mov_b32_e32 v9, v0
	v_mov_b32_e32 v10, v0
	v_mov_b32_e32 v11, v0
	v_mov_b32_e32 v12, v0
	v_mov_b32_e32 v13, v0
	v_mov_b32_e32 v14, v0
	v_mov_b32_e32 v15, v0
	v_mov_b32_e32 v16, v0
	v_mov_b32_e32 v17, v0
	v_mov_b32_e32 v18, v0
	v_mov_b32_e32 v19, v0
	v_mov_b32_e32 v20, v0
	v_mov_b32_e32 v21, v0
	v_mov_b32_e32 v22, v0
	v_mov_b32_e32 v23, v0
	v_mov_b32_e32 v24, v0
	v_mov_b32_e32 v25, v0
	v_mov_b32_e32 v26, v0
	v_mov_b32_e32 v27, v0
	v_mov_b32_e32 v28, v0
	v_mov_b32_e32 v29, v0
	v_mov_b32_e32 v30, v0
	v_mov_b32_e32 v31, v0
	v_mov_b32_e32 v32, v0
	v_mov_b32_e32 v33, v0
	v_mov_b32_e32 v34, v0
	v_mov_b32_e32 v35, v0
	v_mov_b32_e32 v36, v0
	v_mov_b32_e32 v37, v0
	v_mov_b32_e32 v38, v0
	v_mov_b32_e32 v39, v0
	v_mov_b32_e32 v40, v0
	v_mov_b32_e32 v41, v0
	v_mov_b32_e32 v42, v0
	v_mov_b32_e32 v43, v0
	v_mov_b32_e32 v44, v0
	v_mov_b32_e32 v45, v0
	v_mov_b32_e32 v46, v0
	v_mov_b32_e32 v47, v0
	v_mov_b32_e32 v48, v0
	v_mov_b32_e32 v49, v0
	v_mov_b32_e32 v50, v0
	v_mov_b32_e32 v51, v0
	v_mov_b32_e32 v52, v0
	v_mov_b32_e32 v53, v0
	v_mov_b32_e32 v54, v0
	v_mov_b32_e32 v55, v0
	v_mov_b32_e32 v56, v0
	v_mov_b32_e32 v57, v0
	v_mov_b32_e32 v58, v0
	v_mov_b32_e32 v59, v0
	v_mov_b32_e32 v60, v0
	v_mov_b32_e32 v61, v0
	v_mov_b32_e32 v62, v0
	v_mov_b32_e32 v63, v0
	v_mov_b32_e32 v64, v0
	v_mov_b32_e32 v65, v0
	v_mov_b32_e32 v66, v0
	v_mov_b32_e32 v67, v0
	v_mov_b32_e32 v68, v0
	v_mov_b32_e32 v69, v0
	v_mov_b32_e32 v70, v0
	v_mov_b32_e32 v71, v0
	v_mov_b32_e32 v72, v0
	v_mov_b32_e32 v73, v0
	v_mov_b32_e32 v74, v0
	v_mov_b32_e32 v75, v0
	v_mov_b32_e32 v76, v0
	v_mov_b32_e32 v77, v0
	v_mov_b32_e32 v78, v0
	v_mov_b32_e32 v79, v0
	v_mov_b32_e32 v80, v0
	v_mov_b32_e32 v81, v0
	v_mov_b32_e32 v82, v0
	v_mov_b32_e32 v83, v0
	v_mov_b32_e32 v84, v0
	v_mov_b32_e32 v85, v0
	v_mov_b32_e32 v86, v0
	v_mov_b32_e32 v87, v0
	v_mov_b32_e32 v88, v0
	v_mov_b32_e32 v89, v0
	v_mov_b32_e32 v90, v0
	v_mov_b32_e32 v91, v0
	v_mov_b32_e32 v92, v0
	v_mov_b32_e32 v93, v0
	v_mov_b32_e32 v94, v0
	v_mov_b32_e32 v95, v0
	v_mov_b32_e32 v96, v0
	v_mov_b32_e32 v97, v0
	v_mov_b32_e32 v98, v0
	v_mov_b32_e32 v99, v0
	v_mov_b32_e32 v100, v0
	v_mov_b32_e32 v101, v0
	v_mov_b32_e32 v102, v0
	v_mov_b32_e32 v103, v0
	v_mov_b32_e32 v104, v0
	v_mov_b32_e32 v105, v0
	v_mov_b32_e32 v106, v0
	v_mov_b32_e32 v107, v0
	v_mov_b32_e32 v108, v0
	v_mov_b32_e32 v109, v0
	v_mov_b32_e32 v110, v0
	v_mov_b32_e32 v111, v0
	v_mov_b32_e32 v112, v0
	v_mov_b32_e32 v113, v0
	v_mov_b32_e32 v114, v0
	v_mov_b32_e32 v115, v0
	v_mov_b32_e32 v116, v0
	v_mov_b32_e32 v117, v0
	v_mov_b32_e32 v118, v0
	v_mov_b32_e32 v119, v0
	v_mov_b32_e32 v120, v0
	v_mov_b32_e32 v121, v0
	v_mov_b32_e32 v122, v0
	v_mov_b32_e32 v123, v0
	v_mov_b32_e32 v124, v0
	v_mov_b32_e32 v125, v0
	v_mov_b32_e32 v126, v0
	v_mov_b32_e32 v127, v0
	s_waitcnt vmcnt(8)
	s_branch .Lf1_after_vm

; #define RAW_BARRIER() do { asm volatile("s_waitcnt lgkmcnt(0)" ::: "memory"); __builtin_amdgcn_s_barrier(); } while (0)
;   DI u16* kt() const { return (u16*)(ws + O_KT); }
; template <class DescFn, class EpiFn>
; DI void gemm_stream(unsigned char* smem, const int wv, const int start, const int stride, const int end, const int ldb, const int nk, DescFn&& desc, EpiFn&& mkepi) {
;     ...
;     for (int kt = 0; kt < nk; ++kt) {
;       const int buf = kt & 1;
;       asm volatile("s_waitcnt vmcnt(0)" ::: "memory");
;       RAW_BARRIER();
;       if (wave < 4) {
;         if (kt + 1 < nk) { DMA(cur, kt + 1, buf ^ 1); }
;         else if (has_next) { DMA(nxt, 0, 0); }
;       }
.Lf1_after_vm:
	s_waitcnt lgkmcnt(0)
	s_and_b32 s19, s18, 1
	s_andn2_b64 vcc, exec, s[40:41]
	s_barrier
	s_cbranch_vccnz .LBB0_189
	s_cmpk_eq_i32 s10, 0x780
	s_mov_b64 s[12:13], -1
	s_cbranch_scc1 .LBB0_186
	s_lshl_b32 s12, s19, 16
	s_xor_b32 s12, s12, 0x10000
	s_or_b32 s12, s50, s12
	v_lshl_add_u64 v[128:129], v[204:205], 0, s[10:11]
	v_lshl_add_u64 v[130:131], v[128:129], 0, s[44:45]
	s_mov_b32 m0, s12
	s_mov_b64 s[22:23], 0x4080
	global_load_lds_dwordx4 v[130:131], off
	v_lshl_add_u64 v[130:131], v[202:203], 0, s[10:11]
	v_lshl_add_u64 v[132:133], v[130:131], 0, s[22:23]
	s_add_i32 m0, s12, 0x400
	s_mov_b64 s[22:23], 0x8080
	global_load_lds_dwordx4 v[132:133], off
	v_lshl_add_u64 v[132:133], v[128:129], 0, s[22:23]
	s_add_i32 m0, s12, 0x800
	s_mov_b64 s[22:23], 0xc080
	global_load_lds_dwordx4 v[132:133], off
	v_lshl_add_u64 v[132:133], v[130:131], 0, s[22:23]
	s_add_i32 m0, s12, 0xc00
	s_mov_b64 s[22:23], 0x10080
	global_load_lds_dwordx4 v[132:133], off
	v_lshl_add_u64 v[132:133], v[128:129], 0, s[22:23]
	s_add_i32 m0, s12, 0x1000
	s_mov_b64 s[22:23], 0x14080
	global_load_lds_dwordx4 v[132:133], off
	v_lshl_add_u64 v[132:133], v[130:131], 0, s[22:23]
	s_add_i32 m0, s12, 0x1400
	s_mov_b64 s[22:23], 0x18080
	global_load_lds_dwordx4 v[132:133], off
	v_lshl_add_u64 v[128:129], v[128:129], 0, s[22:23]
	s_add_i32 m0, s12, 0x1800
	s_mov_b64 s[22:23], 0x1c080
	global_load_lds_dwordx4 v[128:129], off
	v_lshl_add_u64 v[128:129], v[130:131], 0, s[22:23]
	s_add_i32 m0, s12, 0x1c00
	s_mov_b64 s[12:13], 0
	global_load_lds_dwordx4 v[128:129], off
